# phase7 GEMM epilogue: 16 x-row loads issued up front into dead accumulator registers, counted waits, DPP row-sum instead of bpermute chain; more DPP reductions in PEER, permlane16_swap
# speedup vs baseline: 1.2103x; 1.0164x over previous
.LBB0_963:
	s_waitcnt lgkmcnt(0)
	s_add_i32 s99, s4, 0xffffc000
	s_cmp_lt_i32 s4, s16
	s_cselect_b32 s0, s64, s66
	s_cselect_b32 s1, s65, s67
	s_cselect_b32 s98, s4, s99
	s_lshl_b32 s98, s98, 12
	s_add_u32 s0, s0, s98
	s_addc_u32 s1, s1, 0
	v_lshrrev_b32_e32 v13, 5, v6
	v_lshl_add_u32 v14, v13, 12, v128
	global_load_dwordx4 v[64:67], v14, s[0:1]
	s_add_u32 s0, s0, 0x8000
	s_addc_u32 s1, s1, 0
	global_load_dwordx4 v[68:71], v14, s[0:1]
	s_add_u32 s0, s0, 0x8000
	s_addc_u32 s1, s1, 0
	global_load_dwordx4 v[72:75], v14, s[0:1]
	s_add_u32 s0, s0, 0x8000
	s_addc_u32 s1, s1, 0
	global_load_dwordx4 v[76:79], v14, s[0:1]
	s_add_u32 s0, s0, 0x8000
	s_addc_u32 s1, s1, 0
	global_load_dwordx4 v[80:83], v14, s[0:1]
	s_add_u32 s0, s0, 0x8000
	s_addc_u32 s1, s1, 0
	global_load_dwordx4 v[84:87], v14, s[0:1]
	s_add_u32 s0, s0, 0x8000
	s_addc_u32 s1, s1, 0
	global_load_dwordx4 v[88:91], v14, s[0:1]
	s_add_u32 s0, s0, 0x8000
	s_addc_u32 s1, s1, 0
	global_load_dwordx4 v[92:95], v14, s[0:1]
	s_add_u32 s0, s0, 0x8000
	s_addc_u32 s1, s1, 0
	global_load_dwordx4 v[96:99], v14, s[0:1]
	s_add_u32 s0, s0, 0x8000
	s_addc_u32 s1, s1, 0
	global_load_dwordx4 v[100:103], v14, s[0:1]
	s_add_u32 s0, s0, 0x8000
	s_addc_u32 s1, s1, 0
	global_load_dwordx4 v[104:107], v14, s[0:1]
	s_add_u32 s0, s0, 0x8000
	s_addc_u32 s1, s1, 0
	global_load_dwordx4 v[108:111], v14, s[0:1]
	s_add_u32 s0, s0, 0x8000
	s_addc_u32 s1, s1, 0
	global_load_dwordx4 v[112:115], v14, s[0:1]
	s_add_u32 s0, s0, 0x8000
	s_addc_u32 s1, s1, 0
	global_load_dwordx4 v[116:119], v14, s[0:1]
	s_add_u32 s0, s0, 0x8000
	s_addc_u32 s1, s1, 0
	global_load_dwordx4 v[120:123], v14, s[0:1]
	s_add_u32 s0, s0, 0x8000
	s_addc_u32 s1, s1, 0
	global_load_dwordx4 v[124:127], v14, s[0:1]
	v_lshlrev_b32_e32 v19, 2, v13
	v_lshlrev_b32_e32 v18, 9, v13
	v_bitop3_b32 v19, v19, v7, 16 bitop3:0x6c
	v_lshl_or_b32 v15, v19, 2, v18
	v_add_u32_e32 v4, s4, v13
	v_mov_b32_e32 v5, 0
	s_mov_b32 s98, 0
	s_mov_b32 s99, -1
	ds_read_b128 v[18:21], v15
	s_waitcnt vmcnt(15) lgkmcnt(0)
	v_pk_add_f32 v[64:65], v[18:19], v[64:65]
	v_pk_add_f32 v[66:67], v[20:21], v[66:67]
	v_pk_mul_f32 v[18:19], v[64:65], v[64:65]
	v_pk_mul_f32 v[20:21], v[66:67], v[66:67]
	v_add_f32_e32 v18, v18, v19
	v_add_f32_e32 v18, v18, v20
	v_add_f32_e32 v18, v18, v21
	v_lshlrev_b64 v[16:17], 12, v[4:5]
	v_lshl_add_u64 v[16:17], v[2:3], 0, v[16:17]
	global_store_dwordx4 v[16:17], v[64:67], off
	v_cvt_pk_bf16_f32 v20, v64, v65
	v_cvt_pk_bf16_f32 v21, v66, v67
	v_lshlrev_b64 v[16:17], 11, v[4:5]
	v_lshl_add_u64 v[16:17], v[0:1], 0, v[16:17]
	global_store_dwordx2 v[16:17], v[20:21], off
	v_add_f32_dpp v19, v18, v18 quad_perm:[1,0,3,2] row_mask:0xf bank_mask:0xf
	s_nop 1
	v_add_f32_dpp v18, v19, v19 quad_perm:[2,3,0,1] row_mask:0xf bank_mask:0xf
	s_nop 1
	v_add_f32_dpp v19, v18, v18 row_half_mirror row_mask:0xf bank_mask:0xf
	s_nop 1
	v_add_f32_dpp v18, v19, v19 row_mirror row_mask:0xf bank_mask:0xf
	s_nop 1
	v_readlane_b32 s100, v18, 16
	v_readlane_b32 s101, v18, 48
	v_lshl_add_u64 v[16:17], v[4:5], 2, s[8:9]
	s_nop 0
	v_mov_b32_e32 v19, s100
	v_mov_b32_e32 v20, s101
	v_cndmask_b32_e64 v19, v19, v20, s[98:99]
	v_add_f32_e32 v18, v18, v19
	s_and_saveexec_b64 s[0:1], vcc
	global_store_dword v[16:17], v18, off
	s_or_b64 exec, exec, s[0:1]
	v_add_u32_e32 v4, 8, v4
	ds_read_b128 v[18:21], v15 offset:4096
	s_waitcnt vmcnt(16) lgkmcnt(0)
	v_pk_add_f32 v[68:69], v[18:19], v[68:69]
	v_pk_add_f32 v[70:71], v[20:21], v[70:71]
	v_pk_mul_f32 v[18:19], v[68:69], v[68:69]
	v_pk_mul_f32 v[20:21], v[70:71], v[70:71]
	v_add_f32_e32 v18, v18, v19
	v_add_f32_e32 v18, v18, v20
	v_add_f32_e32 v18, v18, v21
	v_lshlrev_b64 v[16:17], 12, v[4:5]
	v_lshl_add_u64 v[16:17], v[2:3], 0, v[16:17]
	global_store_dwordx4 v[16:17], v[68:71], off
	v_cvt_pk_bf16_f32 v20, v68, v69
	v_cvt_pk_bf16_f32 v21, v70, v71
	v_lshlrev_b64 v[16:17], 11, v[4:5]
	v_lshl_add_u64 v[16:17], v[0:1], 0, v[16:17]
	global_store_dwordx2 v[16:17], v[20:21], off
	v_add_f32_dpp v19, v18, v18 quad_perm:[1,0,3,2] row_mask:0xf bank_mask:0xf
	s_nop 1
	v_add_f32_dpp v18, v19, v19 quad_perm:[2,3,0,1] row_mask:0xf bank_mask:0xf
	s_nop 1
	v_add_f32_dpp v19, v18, v18 row_half_mirror row_mask:0xf bank_mask:0xf
	s_nop 1
	v_add_f32_dpp v18, v19, v19 row_mirror row_mask:0xf bank_mask:0xf
	s_nop 1
	v_readlane_b32 s100, v18, 16
	v_readlane_b32 s101, v18, 48
	v_lshl_add_u64 v[16:17], v[4:5], 2, s[8:9]
	s_nop 0
	v_mov_b32_e32 v19, s100
	v_mov_b32_e32 v20, s101
	v_cndmask_b32_e64 v19, v19, v20, s[98:99]
	v_add_f32_e32 v18, v18, v19
	s_and_saveexec_b64 s[0:1], vcc
	global_store_dword v[16:17], v18, off
	s_or_b64 exec, exec, s[0:1]
	v_add_u32_e32 v4, 8, v4
	ds_read_b128 v[18:21], v15 offset:8192
	s_waitcnt vmcnt(17) lgkmcnt(0)
	v_pk_add_f32 v[72:73], v[18:19], v[72:73]
	v_pk_add_f32 v[74:75], v[20:21], v[74:75]
	v_pk_mul_f32 v[18:19], v[72:73], v[72:73]
	v_pk_mul_f32 v[20:21], v[74:75], v[74:75]
	v_add_f32_e32 v18, v18, v19
	v_add_f32_e32 v18, v18, v20
	v_add_f32_e32 v18, v18, v21
	v_lshlrev_b64 v[16:17], 12, v[4:5]
	v_lshl_add_u64 v[16:17], v[2:3], 0, v[16:17]
	global_store_dwordx4 v[16:17], v[72:75], off
	v_cvt_pk_bf16_f32 v20, v72, v73
	v_cvt_pk_bf16_f32 v21, v74, v75
	v_lshlrev_b64 v[16:17], 11, v[4:5]
	v_lshl_add_u64 v[16:17], v[0:1], 0, v[16:17]
	global_store_dwordx2 v[16:17], v[20:21], off
	v_add_f32_dpp v19, v18, v18 quad_perm:[1,0,3,2] row_mask:0xf bank_mask:0xf
	s_nop 1
	v_add_f32_dpp v18, v19, v19 quad_perm:[2,3,0,1] row_mask:0xf bank_mask:0xf
	s_nop 1
	v_add_f32_dpp v19, v18, v18 row_half_mirror row_mask:0xf bank_mask:0xf
	s_nop 1
	v_add_f32_dpp v18, v19, v19 row_mirror row_mask:0xf bank_mask:0xf
	s_nop 1
	v_readlane_b32 s100, v18, 16
	v_readlane_b32 s101, v18, 48
	v_lshl_add_u64 v[16:17], v[4:5], 2, s[8:9]
	s_nop 0
	v_mov_b32_e32 v19, s100
	v_mov_b32_e32 v20, s101
	v_cndmask_b32_e64 v19, v19, v20, s[98:99]
	v_add_f32_e32 v18, v18, v19
	s_and_saveexec_b64 s[0:1], vcc
	global_store_dword v[16:17], v18, off
	s_or_b64 exec, exec, s[0:1]
	v_add_u32_e32 v4, 8, v4
	ds_read_b128 v[18:21], v15 offset:12288
	s_waitcnt vmcnt(18) lgkmcnt(0)
	v_pk_add_f32 v[76:77], v[18:19], v[76:77]
	v_pk_add_f32 v[78:79], v[20:21], v[78:79]
	v_pk_mul_f32 v[18:19], v[76:77], v[76:77]
	v_pk_mul_f32 v[20:21], v[78:79], v[78:79]
	v_add_f32_e32 v18, v18, v19
	v_add_f32_e32 v18, v18, v20
	v_add_f32_e32 v18, v18, v21
	v_lshlrev_b64 v[16:17], 12, v[4:5]
	v_lshl_add_u64 v[16:17], v[2:3], 0, v[16:17]
	global_store_dwordx4 v[16:17], v[76:79], off
	v_cvt_pk_bf16_f32 v20, v76, v77
	v_cvt_pk_bf16_f32 v21, v78, v79
	v_lshlrev_b64 v[16:17], 11, v[4:5]
	v_lshl_add_u64 v[16:17], v[0:1], 0, v[16:17]
	global_store_dwordx2 v[16:17], v[20:21], off
	v_add_f32_dpp v19, v18, v18 quad_perm:[1,0,3,2] row_mask:0xf bank_mask:0xf
	s_nop 1
	v_add_f32_dpp v18, v19, v19 quad_perm:[2,3,0,1] row_mask:0xf bank_mask:0xf
	s_nop 1
	v_add_f32_dpp v19, v18, v18 row_half_mirror row_mask:0xf bank_mask:0xf
	s_nop 1
	v_add_f32_dpp v18, v19, v19 row_mirror row_mask:0xf bank_mask:0xf
	s_nop 1
	v_readlane_b32 s100, v18, 16
	v_readlane_b32 s101, v18, 48
	v_lshl_add_u64 v[16:17], v[4:5], 2, s[8:9]
	s_nop 0
	v_mov_b32_e32 v19, s100
	v_mov_b32_e32 v20, s101
	v_cndmask_b32_e64 v19, v19, v20, s[98:99]
	v_add_f32_e32 v18, v18, v19
	s_and_saveexec_b64 s[0:1], vcc
	global_store_dword v[16:17], v18, off
	s_or_b64 exec, exec, s[0:1]
	v_add_u32_e32 v4, 8, v4
	ds_read_b128 v[18:21], v15 offset:16384
	s_waitcnt vmcnt(19) lgkmcnt(0)
	v_pk_add_f32 v[80:81], v[18:19], v[80:81]
	v_pk_add_f32 v[82:83], v[20:21], v[82:83]
	v_pk_mul_f32 v[18:19], v[80:81], v[80:81]
	v_pk_mul_f32 v[20:21], v[82:83], v[82:83]
	v_add_f32_e32 v18, v18, v19
	v_add_f32_e32 v18, v18, v20
	v_add_f32_e32 v18, v18, v21
	v_lshlrev_b64 v[16:17], 12, v[4:5]
	v_lshl_add_u64 v[16:17], v[2:3], 0, v[16:17]
	global_store_dwordx4 v[16:17], v[80:83], off
	v_cvt_pk_bf16_f32 v20, v80, v81
	v_cvt_pk_bf16_f32 v21, v82, v83
	v_lshlrev_b64 v[16:17], 11, v[4:5]
	v_lshl_add_u64 v[16:17], v[0:1], 0, v[16:17]
	global_store_dwordx2 v[16:17], v[20:21], off
	v_add_f32_dpp v19, v18, v18 quad_perm:[1,0,3,2] row_mask:0xf bank_mask:0xf
	s_nop 1
	v_add_f32_dpp v18, v19, v19 quad_perm:[2,3,0,1] row_mask:0xf bank_mask:0xf
	s_nop 1
	v_add_f32_dpp v19, v18, v18 row_half_mirror row_mask:0xf bank_mask:0xf
	s_nop 1
	v_add_f32_dpp v18, v19, v19 row_mirror row_mask:0xf bank_mask:0xf
	s_nop 1
	v_readlane_b32 s100, v18, 16
	v_readlane_b32 s101, v18, 48
	v_lshl_add_u64 v[16:17], v[4:5], 2, s[8:9]
	s_nop 0
	v_mov_b32_e32 v19, s100
	v_mov_b32_e32 v20, s101
	v_cndmask_b32_e64 v19, v19, v20, s[98:99]
	v_add_f32_e32 v18, v18, v19
	s_and_saveexec_b64 s[0:1], vcc
	global_store_dword v[16:17], v18, off
	s_or_b64 exec, exec, s[0:1]
	v_add_u32_e32 v4, 8, v4
	ds_read_b128 v[18:21], v15 offset:20480
	s_waitcnt vmcnt(20) lgkmcnt(0)
	v_pk_add_f32 v[84:85], v[18:19], v[84:85]
	v_pk_add_f32 v[86:87], v[20:21], v[86:87]
	v_pk_mul_f32 v[18:19], v[84:85], v[84:85]
	v_pk_mul_f32 v[20:21], v[86:87], v[86:87]
	v_add_f32_e32 v18, v18, v19
	v_add_f32_e32 v18, v18, v20
	v_add_f32_e32 v18, v18, v21
	v_lshlrev_b64 v[16:17], 12, v[4:5]
	v_lshl_add_u64 v[16:17], v[2:3], 0, v[16:17]
	global_store_dwordx4 v[16:17], v[84:87], off
	v_cvt_pk_bf16_f32 v20, v84, v85
	v_cvt_pk_bf16_f32 v21, v86, v87
	v_lshlrev_b64 v[16:17], 11, v[4:5]
	v_lshl_add_u64 v[16:17], v[0:1], 0, v[16:17]
	global_store_dwordx2 v[16:17], v[20:21], off
	v_add_f32_dpp v19, v18, v18 quad_perm:[1,0,3,2] row_mask:0xf bank_mask:0xf
	s_nop 1
	v_add_f32_dpp v18, v19, v19 quad_perm:[2,3,0,1] row_mask:0xf bank_mask:0xf
	s_nop 1
	v_add_f32_dpp v19, v18, v18 row_half_mirror row_mask:0xf bank_mask:0xf
	s_nop 1
	v_add_f32_dpp v18, v19, v19 row_mirror row_mask:0xf bank_mask:0xf
	s_nop 1
	v_readlane_b32 s100, v18, 16
	v_readlane_b32 s101, v18, 48
	v_lshl_add_u64 v[16:17], v[4:5], 2, s[8:9]
	s_nop 0
	v_mov_b32_e32 v19, s100
	v_mov_b32_e32 v20, s101
	v_cndmask_b32_e64 v19, v19, v20, s[98:99]
	v_add_f32_e32 v18, v18, v19
	s_and_saveexec_b64 s[0:1], vcc
	global_store_dword v[16:17], v18, off
	s_or_b64 exec, exec, s[0:1]
	v_add_u32_e32 v4, 8, v4
	ds_read_b128 v[18:21], v15 offset:24576
	s_waitcnt vmcnt(21) lgkmcnt(0)
	v_pk_add_f32 v[88:89], v[18:19], v[88:89]
	v_pk_add_f32 v[90:91], v[20:21], v[90:91]
	v_pk_mul_f32 v[18:19], v[88:89], v[88:89]
	v_pk_mul_f32 v[20:21], v[90:91], v[90:91]
	v_add_f32_e32 v18, v18, v19
	v_add_f32_e32 v18, v18, v20
	v_add_f32_e32 v18, v18, v21
	v_lshlrev_b64 v[16:17], 12, v[4:5]
	v_lshl_add_u64 v[16:17], v[2:3], 0, v[16:17]
	global_store_dwordx4 v[16:17], v[88:91], off
	v_cvt_pk_bf16_f32 v20, v88, v89
	v_cvt_pk_bf16_f32 v21, v90, v91
	v_lshlrev_b64 v[16:17], 11, v[4:5]
	v_lshl_add_u64 v[16:17], v[0:1], 0, v[16:17]
	global_store_dwordx2 v[16:17], v[20:21], off
	v_add_f32_dpp v19, v18, v18 quad_perm:[1,0,3,2] row_mask:0xf bank_mask:0xf
	s_nop 1
	v_add_f32_dpp v18, v19, v19 quad_perm:[2,3,0,1] row_mask:0xf bank_mask:0xf
	s_nop 1
	v_add_f32_dpp v19, v18, v18 row_half_mirror row_mask:0xf bank_mask:0xf
	s_nop 1
	v_add_f32_dpp v18, v19, v19 row_mirror row_mask:0xf bank_mask:0xf
	s_nop 1
	v_readlane_b32 s100, v18, 16
	v_readlane_b32 s101, v18, 48
	v_lshl_add_u64 v[16:17], v[4:5], 2, s[8:9]
	s_nop 0
	v_mov_b32_e32 v19, s100
	v_mov_b32_e32 v20, s101
	v_cndmask_b32_e64 v19, v19, v20, s[98:99]
	v_add_f32_e32 v18, v18, v19
	s_and_saveexec_b64 s[0:1], vcc
	global_store_dword v[16:17], v18, off
	s_or_b64 exec, exec, s[0:1]
	v_add_u32_e32 v4, 8, v4
	ds_read_b128 v[18:21], v15 offset:28672
	s_waitcnt vmcnt(22) lgkmcnt(0)
	v_pk_add_f32 v[92:93], v[18:19], v[92:93]
	v_pk_add_f32 v[94:95], v[20:21], v[94:95]
	v_pk_mul_f32 v[18:19], v[92:93], v[92:93]
	v_pk_mul_f32 v[20:21], v[94:95], v[94:95]
	v_add_f32_e32 v18, v18, v19
	v_add_f32_e32 v18, v18, v20
	v_add_f32_e32 v18, v18, v21
	v_lshlrev_b64 v[16:17], 12, v[4:5]
	v_lshl_add_u64 v[16:17], v[2:3], 0, v[16:17]
	global_store_dwordx4 v[16:17], v[92:95], off
	v_cvt_pk_bf16_f32 v20, v92, v93
	v_cvt_pk_bf16_f32 v21, v94, v95
	v_lshlrev_b64 v[16:17], 11, v[4:5]
	v_lshl_add_u64 v[16:17], v[0:1], 0, v[16:17]
	global_store_dwordx2 v[16:17], v[20:21], off
	v_add_f32_dpp v19, v18, v18 quad_perm:[1,0,3,2] row_mask:0xf bank_mask:0xf
	s_nop 1
	v_add_f32_dpp v18, v19, v19 quad_perm:[2,3,0,1] row_mask:0xf bank_mask:0xf
	s_nop 1
	v_add_f32_dpp v19, v18, v18 row_half_mirror row_mask:0xf bank_mask:0xf
	s_nop 1
	v_add_f32_dpp v18, v19, v19 row_mirror row_mask:0xf bank_mask:0xf
	s_nop 1
	v_readlane_b32 s100, v18, 16
	v_readlane_b32 s101, v18, 48
	v_lshl_add_u64 v[16:17], v[4:5], 2, s[8:9]
	s_nop 0
	v_mov_b32_e32 v19, s100
	v_mov_b32_e32 v20, s101
	v_cndmask_b32_e64 v19, v19, v20, s[98:99]
	v_add_f32_e32 v18, v18, v19
	s_and_saveexec_b64 s[0:1], vcc
	global_store_dword v[16:17], v18, off
	s_or_b64 exec, exec, s[0:1]
	v_add_u32_e32 v4, 8, v4
	ds_read_b128 v[18:21], v15 offset:32768
	s_waitcnt vmcnt(23) lgkmcnt(0)
	v_pk_add_f32 v[96:97], v[18:19], v[96:97]
	v_pk_add_f32 v[98:99], v[20:21], v[98:99]
	v_pk_mul_f32 v[18:19], v[96:97], v[96:97]
	v_pk_mul_f32 v[20:21], v[98:99], v[98:99]
	v_add_f32_e32 v18, v18, v19
	v_add_f32_e32 v18, v18, v20
	v_add_f32_e32 v18, v18, v21
	v_lshlrev_b64 v[16:17], 12, v[4:5]
	v_lshl_add_u64 v[16:17], v[2:3], 0, v[16:17]
	global_store_dwordx4 v[16:17], v[96:99], off
	v_cvt_pk_bf16_f32 v20, v96, v97
	v_cvt_pk_bf16_f32 v21, v98, v99
	v_lshlrev_b64 v[16:17], 11, v[4:5]
	v_lshl_add_u64 v[16:17], v[0:1], 0, v[16:17]
	global_store_dwordx2 v[16:17], v[20:21], off
	v_add_f32_dpp v19, v18, v18 quad_perm:[1,0,3,2] row_mask:0xf bank_mask:0xf
	s_nop 1
	v_add_f32_dpp v18, v19, v19 quad_perm:[2,3,0,1] row_mask:0xf bank_mask:0xf
	s_nop 1
	v_add_f32_dpp v19, v18, v18 row_half_mirror row_mask:0xf bank_mask:0xf
	s_nop 1
	v_add_f32_dpp v18, v19, v19 row_mirror row_mask:0xf bank_mask:0xf
	s_nop 1
	v_readlane_b32 s100, v18, 16
	v_readlane_b32 s101, v18, 48
	v_lshl_add_u64 v[16:17], v[4:5], 2, s[8:9]
	s_nop 0
	v_mov_b32_e32 v19, s100
	v_mov_b32_e32 v20, s101
	v_cndmask_b32_e64 v19, v19, v20, s[98:99]
	v_add_f32_e32 v18, v18, v19
	s_and_saveexec_b64 s[0:1], vcc
	global_store_dword v[16:17], v18, off
	s_or_b64 exec, exec, s[0:1]
	v_add_u32_e32 v4, 8, v4
	ds_read_b128 v[18:21], v15 offset:36864
	s_waitcnt vmcnt(24) lgkmcnt(0)
	v_pk_add_f32 v[100:101], v[18:19], v[100:101]
	v_pk_add_f32 v[102:103], v[20:21], v[102:103]
	v_pk_mul_f32 v[18:19], v[100:101], v[100:101]
	v_pk_mul_f32 v[20:21], v[102:103], v[102:103]
	v_add_f32_e32 v18, v18, v19
	v_add_f32_e32 v18, v18, v20
	v_add_f32_e32 v18, v18, v21
	v_lshlrev_b64 v[16:17], 12, v[4:5]
	v_lshl_add_u64 v[16:17], v[2:3], 0, v[16:17]
	global_store_dwordx4 v[16:17], v[100:103], off
	v_cvt_pk_bf16_f32 v20, v100, v101
	v_cvt_pk_bf16_f32 v21, v102, v103
	v_lshlrev_b64 v[16:17], 11, v[4:5]
	v_lshl_add_u64 v[16:17], v[0:1], 0, v[16:17]
	global_store_dwordx2 v[16:17], v[20:21], off
	v_add_f32_dpp v19, v18, v18 quad_perm:[1,0,3,2] row_mask:0xf bank_mask:0xf
	s_nop 1
	v_add_f32_dpp v18, v19, v19 quad_perm:[2,3,0,1] row_mask:0xf bank_mask:0xf
	s_nop 1
	v_add_f32_dpp v19, v18, v18 row_half_mirror row_mask:0xf bank_mask:0xf
	s_nop 1
	v_add_f32_dpp v18, v19, v19 row_mirror row_mask:0xf bank_mask:0xf
	s_nop 1
	v_readlane_b32 s100, v18, 16
	v_readlane_b32 s101, v18, 48
	v_lshl_add_u64 v[16:17], v[4:5], 2, s[8:9]
	s_nop 0
	v_mov_b32_e32 v19, s100
	v_mov_b32_e32 v20, s101
	v_cndmask_b32_e64 v19, v19, v20, s[98:99]
	v_add_f32_e32 v18, v18, v19
	s_and_saveexec_b64 s[0:1], vcc
	global_store_dword v[16:17], v18, off
	s_or_b64 exec, exec, s[0:1]
	v_add_u32_e32 v4, 8, v4
	ds_read_b128 v[18:21], v15 offset:40960
	s_waitcnt vmcnt(25) lgkmcnt(0)
	v_pk_add_f32 v[104:105], v[18:19], v[104:105]
	v_pk_add_f32 v[106:107], v[20:21], v[106:107]
	v_pk_mul_f32 v[18:19], v[104:105], v[104:105]
	v_pk_mul_f32 v[20:21], v[106:107], v[106:107]
	v_add_f32_e32 v18, v18, v19
	v_add_f32_e32 v18, v18, v20
	v_add_f32_e32 v18, v18, v21
	v_lshlrev_b64 v[16:17], 12, v[4:5]
	v_lshl_add_u64 v[16:17], v[2:3], 0, v[16:17]
	global_store_dwordx4 v[16:17], v[104:107], off
	v_cvt_pk_bf16_f32 v20, v104, v105
	v_cvt_pk_bf16_f32 v21, v106, v107
	v_lshlrev_b64 v[16:17], 11, v[4:5]
	v_lshl_add_u64 v[16:17], v[0:1], 0, v[16:17]
	global_store_dwordx2 v[16:17], v[20:21], off
	v_add_f32_dpp v19, v18, v18 quad_perm:[1,0,3,2] row_mask:0xf bank_mask:0xf
	s_nop 1
	v_add_f32_dpp v18, v19, v19 quad_perm:[2,3,0,1] row_mask:0xf bank_mask:0xf
	s_nop 1
	v_add_f32_dpp v19, v18, v18 row_half_mirror row_mask:0xf bank_mask:0xf
	s_nop 1
	v_add_f32_dpp v18, v19, v19 row_mirror row_mask:0xf bank_mask:0xf
	s_nop 1
	v_readlane_b32 s100, v18, 16
	v_readlane_b32 s101, v18, 48
	v_lshl_add_u64 v[16:17], v[4:5], 2, s[8:9]
	s_nop 0
	v_mov_b32_e32 v19, s100
	v_mov_b32_e32 v20, s101
	v_cndmask_b32_e64 v19, v19, v20, s[98:99]
	v_add_f32_e32 v18, v18, v19
	s_and_saveexec_b64 s[0:1], vcc
	global_store_dword v[16:17], v18, off
	s_or_b64 exec, exec, s[0:1]
	v_add_u32_e32 v4, 8, v4
	ds_read_b128 v[18:21], v15 offset:45056
	s_waitcnt vmcnt(26) lgkmcnt(0)
	v_pk_add_f32 v[108:109], v[18:19], v[108:109]
	v_pk_add_f32 v[110:111], v[20:21], v[110:111]
	v_pk_mul_f32 v[18:19], v[108:109], v[108:109]
	v_pk_mul_f32 v[20:21], v[110:111], v[110:111]
	v_add_f32_e32 v18, v18, v19
	v_add_f32_e32 v18, v18, v20
	v_add_f32_e32 v18, v18, v21
	v_lshlrev_b64 v[16:17], 12, v[4:5]
	v_lshl_add_u64 v[16:17], v[2:3], 0, v[16:17]
	global_store_dwordx4 v[16:17], v[108:111], off
	v_cvt_pk_bf16_f32 v20, v108, v109
	v_cvt_pk_bf16_f32 v21, v110, v111
	v_lshlrev_b64 v[16:17], 11, v[4:5]
	v_lshl_add_u64 v[16:17], v[0:1], 0, v[16:17]
	global_store_dwordx2 v[16:17], v[20:21], off
	v_add_f32_dpp v19, v18, v18 quad_perm:[1,0,3,2] row_mask:0xf bank_mask:0xf
	s_nop 1
	v_add_f32_dpp v18, v19, v19 quad_perm:[2,3,0,1] row_mask:0xf bank_mask:0xf
	s_nop 1
	v_add_f32_dpp v19, v18, v18 row_half_mirror row_mask:0xf bank_mask:0xf
	s_nop 1
	v_add_f32_dpp v18, v19, v19 row_mirror row_mask:0xf bank_mask:0xf
	s_nop 1
	v_readlane_b32 s100, v18, 16
	v_readlane_b32 s101, v18, 48
	v_lshl_add_u64 v[16:17], v[4:5], 2, s[8:9]
	s_nop 0
	v_mov_b32_e32 v19, s100
	v_mov_b32_e32 v20, s101
	v_cndmask_b32_e64 v19, v19, v20, s[98:99]
	v_add_f32_e32 v18, v18, v19
	s_and_saveexec_b64 s[0:1], vcc
	global_store_dword v[16:17], v18, off
	s_or_b64 exec, exec, s[0:1]
	v_add_u32_e32 v4, 8, v4
	ds_read_b128 v[18:21], v15 offset:49152
	s_waitcnt vmcnt(27) lgkmcnt(0)
	v_pk_add_f32 v[112:113], v[18:19], v[112:113]
	v_pk_add_f32 v[114:115], v[20:21], v[114:115]
	v_pk_mul_f32 v[18:19], v[112:113], v[112:113]
	v_pk_mul_f32 v[20:21], v[114:115], v[114:115]
	v_add_f32_e32 v18, v18, v19
	v_add_f32_e32 v18, v18, v20
	v_add_f32_e32 v18, v18, v21
	v_lshlrev_b64 v[16:17], 12, v[4:5]
	v_lshl_add_u64 v[16:17], v[2:3], 0, v[16:17]
	global_store_dwordx4 v[16:17], v[112:115], off
	v_cvt_pk_bf16_f32 v20, v112, v113
	v_cvt_pk_bf16_f32 v21, v114, v115
	v_lshlrev_b64 v[16:17], 11, v[4:5]
	v_lshl_add_u64 v[16:17], v[0:1], 0, v[16:17]
	global_store_dwordx2 v[16:17], v[20:21], off
	v_add_f32_dpp v19, v18, v18 quad_perm:[1,0,3,2] row_mask:0xf bank_mask:0xf
	s_nop 1
	v_add_f32_dpp v18, v19, v19 quad_perm:[2,3,0,1] row_mask:0xf bank_mask:0xf
	s_nop 1
	v_add_f32_dpp v19, v18, v18 row_half_mirror row_mask:0xf bank_mask:0xf
	s_nop 1
	v_add_f32_dpp v18, v19, v19 row_mirror row_mask:0xf bank_mask:0xf
	s_nop 1
	v_readlane_b32 s100, v18, 16
	v_readlane_b32 s101, v18, 48
	v_lshl_add_u64 v[16:17], v[4:5], 2, s[8:9]
	s_nop 0
	v_mov_b32_e32 v19, s100
	v_mov_b32_e32 v20, s101
	v_cndmask_b32_e64 v19, v19, v20, s[98:99]
	v_add_f32_e32 v18, v18, v19
	s_and_saveexec_b64 s[0:1], vcc
	global_store_dword v[16:17], v18, off
	s_or_b64 exec, exec, s[0:1]
	v_add_u32_e32 v4, 8, v4
	ds_read_b128 v[18:21], v15 offset:53248
	s_waitcnt vmcnt(28) lgkmcnt(0)
	v_pk_add_f32 v[116:117], v[18:19], v[116:117]
	v_pk_add_f32 v[118:119], v[20:21], v[118:119]
	v_pk_mul_f32 v[18:19], v[116:117], v[116:117]
	v_pk_mul_f32 v[20:21], v[118:119], v[118:119]
	v_add_f32_e32 v18, v18, v19
	v_add_f32_e32 v18, v18, v20
	v_add_f32_e32 v18, v18, v21
	v_lshlrev_b64 v[16:17], 12, v[4:5]
	v_lshl_add_u64 v[16:17], v[2:3], 0, v[16:17]
	global_store_dwordx4 v[16:17], v[116:119], off
	v_cvt_pk_bf16_f32 v20, v116, v117
	v_cvt_pk_bf16_f32 v21, v118, v119
	v_lshlrev_b64 v[16:17], 11, v[4:5]
	v_lshl_add_u64 v[16:17], v[0:1], 0, v[16:17]
	global_store_dwordx2 v[16:17], v[20:21], off
	v_add_f32_dpp v19, v18, v18 quad_perm:[1,0,3,2] row_mask:0xf bank_mask:0xf
	s_nop 1
	v_add_f32_dpp v18, v19, v19 quad_perm:[2,3,0,1] row_mask:0xf bank_mask:0xf
	s_nop 1
	v_add_f32_dpp v19, v18, v18 row_half_mirror row_mask:0xf bank_mask:0xf
	s_nop 1
	v_add_f32_dpp v18, v19, v19 row_mirror row_mask:0xf bank_mask:0xf
	s_nop 1
	v_readlane_b32 s100, v18, 16
	v_readlane_b32 s101, v18, 48
	v_lshl_add_u64 v[16:17], v[4:5], 2, s[8:9]
	s_nop 0
	v_mov_b32_e32 v19, s100
	v_mov_b32_e32 v20, s101
	v_cndmask_b32_e64 v19, v19, v20, s[98:99]
	v_add_f32_e32 v18, v18, v19
	s_and_saveexec_b64 s[0:1], vcc
	global_store_dword v[16:17], v18, off
	s_or_b64 exec, exec, s[0:1]
	v_add_u32_e32 v4, 8, v4
	ds_read_b128 v[18:21], v15 offset:57344
	s_waitcnt vmcnt(29) lgkmcnt(0)
	v_pk_add_f32 v[120:121], v[18:19], v[120:121]
	v_pk_add_f32 v[122:123], v[20:21], v[122:123]
	v_pk_mul_f32 v[18:19], v[120:121], v[120:121]
	v_pk_mul_f32 v[20:21], v[122:123], v[122:123]
	v_add_f32_e32 v18, v18, v19
	v_add_f32_e32 v18, v18, v20
	v_add_f32_e32 v18, v18, v21
	v_lshlrev_b64 v[16:17], 12, v[4:5]
	v_lshl_add_u64 v[16:17], v[2:3], 0, v[16:17]
	global_store_dwordx4 v[16:17], v[120:123], off
	v_cvt_pk_bf16_f32 v20, v120, v121
	v_cvt_pk_bf16_f32 v21, v122, v123
	v_lshlrev_b64 v[16:17], 11, v[4:5]
	v_lshl_add_u64 v[16:17], v[0:1], 0, v[16:17]
	global_store_dwordx2 v[16:17], v[20:21], off
	v_add_f32_dpp v19, v18, v18 quad_perm:[1,0,3,2] row_mask:0xf bank_mask:0xf
	s_nop 1
	v_add_f32_dpp v18, v19, v19 quad_perm:[2,3,0,1] row_mask:0xf bank_mask:0xf
	s_nop 1
	v_add_f32_dpp v19, v18, v18 row_half_mirror row_mask:0xf bank_mask:0xf
	s_nop 1
	v_add_f32_dpp v18, v19, v19 row_mirror row_mask:0xf bank_mask:0xf
	s_nop 1
	v_readlane_b32 s100, v18, 16
	v_readlane_b32 s101, v18, 48
	v_lshl_add_u64 v[16:17], v[4:5], 2, s[8:9]
	s_nop 0
	v_mov_b32_e32 v19, s100
	v_mov_b32_e32 v20, s101
	v_cndmask_b32_e64 v19, v19, v20, s[98:99]
	v_add_f32_e32 v18, v18, v19
	s_and_saveexec_b64 s[0:1], vcc
	global_store_dword v[16:17], v18, off
	s_or_b64 exec, exec, s[0:1]
	v_add_u32_e32 v4, 8, v4
	ds_read_b128 v[18:21], v15 offset:61440
	s_waitcnt vmcnt(30) lgkmcnt(0)
	v_pk_add_f32 v[124:125], v[18:19], v[124:125]
	v_pk_add_f32 v[126:127], v[20:21], v[126:127]
	v_pk_mul_f32 v[18:19], v[124:125], v[124:125]
	v_pk_mul_f32 v[20:21], v[126:127], v[126:127]
	v_add_f32_e32 v18, v18, v19
	v_add_f32_e32 v18, v18, v20
	v_add_f32_e32 v18, v18, v21
	v_lshlrev_b64 v[16:17], 12, v[4:5]
	v_lshl_add_u64 v[16:17], v[2:3], 0, v[16:17]
	global_store_dwordx4 v[16:17], v[124:127], off
	v_cvt_pk_bf16_f32 v20, v124, v125
	v_cvt_pk_bf16_f32 v21, v126, v127
	v_lshlrev_b64 v[16:17], 11, v[4:5]
	v_lshl_add_u64 v[16:17], v[0:1], 0, v[16:17]
	global_store_dwordx2 v[16:17], v[20:21], off
	v_add_f32_dpp v19, v18, v18 quad_perm:[1,0,3,2] row_mask:0xf bank_mask:0xf
	s_nop 1
	v_add_f32_dpp v18, v19, v19 quad_perm:[2,3,0,1] row_mask:0xf bank_mask:0xf
	s_nop 1
	v_add_f32_dpp v19, v18, v18 row_half_mirror row_mask:0xf bank_mask:0xf
	s_nop 1
	v_add_f32_dpp v18, v19, v19 row_mirror row_mask:0xf bank_mask:0xf
	s_nop 1
	v_readlane_b32 s100, v18, 16
	v_readlane_b32 s101, v18, 48
	v_lshl_add_u64 v[16:17], v[4:5], 2, s[8:9]
	s_nop 0
	v_mov_b32_e32 v19, s100
	v_mov_b32_e32 v20, s101
	v_cndmask_b32_e64 v19, v19, v20, s[98:99]
	v_add_f32_e32 v18, v18, v19
	s_and_saveexec_b64 s[0:1], vcc
	global_store_dword v[16:17], v18, off
	s_or_b64 exec, exec, s[0:1]
	v_add_u32_e32 v4, 8, v4
	s_branch .LBB0_954

.LBB0_1117:
	v_ashrrev_i32_e32 v97, 31, v96
	v_lshlrev_b64 v[0:1], 12, v[96:97]
	v_lshl_add_u64 v[116:117], v[102:103], 0, v[0:1]
	s_waitcnt lgkmcnt(0)
	global_load_dwordx4 v[12:15], v[116:117], off
	global_load_dwordx4 v[8:11], v[116:117], off offset:16
	global_load_dwordx4 v[4:7], v[116:117], off offset:32
	global_load_dwordx4 v[0:3], v[116:117], off offset:48
	global_load_dwordx4 v[16:19], v[104:105], off offset:48
	global_load_dwordx4 v[20:23], v[104:105], off offset:32
	global_load_dwordx4 v[24:27], v[104:105], off offset:16
	global_load_dwordx4 v[28:31], v[104:105], off
	v_lshlrev_b64 v[118:119], 10, v[96:97]
	v_lshl_add_u64 v[32:33], s[84:85], 0, v[118:119]
	v_lshl_add_u64 v[34:35], v[100:101], 2, v[32:33]
	v_lshl_add_u64 v[32:33], v[98:99], 2, v[32:33]
	global_load_dword v42, v[34:35], off
	global_load_dword v43, v[32:33], off offset:64
	s_mov_b32 s24, 0
	s_waitcnt vmcnt(9)
	v_pk_mul_f32 v[32:33], v[12:13], v[12:13]
	v_pk_mul_f32 v[34:35], v[14:15], v[14:15]
	v_add_f32_e32 v32, v32, v33
	v_add_f32_e32 v32, v32, v34
	s_waitcnt vmcnt(8)
	v_pk_mul_f32 v[36:37], v[8:9], v[8:9]
	v_add_f32_e32 v32, v32, v35
	v_add_f32_e32 v32, v32, v36
	v_pk_mul_f32 v[38:39], v[10:11], v[10:11]
	v_add_f32_e32 v32, v32, v37
	v_add_f32_e32 v32, v32, v38
	s_waitcnt vmcnt(7)
	v_pk_mul_f32 v[40:41], v[4:5], v[4:5]
	v_add_f32_e32 v32, v32, v39
	v_add_f32_e32 v32, v32, v40
	v_pk_mul_f32 v[44:45], v[6:7], v[6:7]
	v_add_f32_e32 v32, v32, v41
	v_add_f32_e32 v32, v32, v44
	s_waitcnt vmcnt(6)
	v_pk_mul_f32 v[46:47], v[0:1], v[0:1]
	v_add_f32_e32 v32, v32, v45
	v_add_f32_e32 v32, v32, v46
	v_pk_mul_f32 v[48:49], v[2:3], v[2:3]
	v_add_f32_e32 v32, v32, v47
	v_add_f32_e32 v32, v32, v48
	v_add_f32_e32 v32, v32, v49
	v_lshl_add_u64 v[36:37], v[112:113], 0, v[118:119]
	v_lshl_add_u64 v[38:39], v[114:115], 0, v[118:119]
	s_nop 1
	v_add_f32_dpp v33, v32, v32 quad_perm:[1,0,3,2] row_mask:0xf bank_mask:0xf
	s_nop 1
	v_add_f32_dpp v32, v33, v33 quad_perm:[2,3,0,1] row_mask:0xf bank_mask:0xf
	s_nop 1
	v_add_f32_dpp v33, v32, v32 row_half_mirror row_mask:0xf bank_mask:0xf
	s_nop 1
	v_add_f32_dpp v32, v33, v33 row_mirror row_mask:0xf bank_mask:0xf
	s_nop 1
	v_readlane_b32 s0, v32, 0
	v_readlane_b32 s1, v32, 16
	v_readlane_b32 s22, v32, 32
	v_readlane_b32 s23, v32, 48
	s_nop 1
	v_mov_b32_e32 v72, s0
	v_add_f32_e32 v72, s1, v72
	v_add_f32_e32 v72, s22, v72
	v_add_f32_e32 v72, s23, v72
	v_mov_b32_e32 v73, 0

.Lpc_unit:
	s_lshl_b32 s0, s17, 11
	s_add_i32 s0, s0, s27
	s_cmp_eq_u32 s17, 8
	s_cselect_b32 s0, s44, s0
	s_lshl_b32 s1, s16, 9
	s_lshl_b32 s24, s0, 12
	s_add_u32 s24, s24, s1
	s_add_u32 s20, s4, s24
	s_addc_u32 s21, s5, 0
	s_lshl_b32 s24, s0, 11
	s_lshr_b32 s1, s1, 1
	s_add_u32 s24, s24, s1
	s_add_u32 s36, s12, s24
	s_addc_u32 s37, s13, 0
	s_lshl_b32 s25, s16, 21
	s_add_u32 s18, s10, s25
	s_addc_u32 s19, s11, 0
	s_lshl_b32 s25, s17, 9
	v_add_u32_e32 v205, s25, v190
	v_add_u32_e32 v206, s25, v202
	ds_read_b128 v[64:67], v205
	ds_read_b128 v[68:71], v205 offset:16
	ds_read_b128 v[72:75], v205 offset:32
	ds_read_b128 v[76:79], v205 offset:48
	ds_read_b128 v[112:115], v205 offset:4608
	ds_read_b128 v[116:119], v205 offset:4624
	ds_read_b128 v[120:123], v205 offset:4640
	ds_read_b128 v[124:127], v205 offset:4656
	global_load_dwordx2 v[208:209], v211, s[20:21]
	s_waitcnt lgkmcnt(4)
	v_add_u32_e32 v64, v64, v188
	v_add_u32_e32 v65, v65, v188
	v_add_u32_e32 v66, v66, v188
	v_add_u32_e32 v67, v67, v188
	v_add_u32_e32 v68, v68, v188
	v_add_u32_e32 v69, v69, v188
	v_add_u32_e32 v70, v70, v188
	v_add_u32_e32 v71, v71, v188
	v_add_u32_e32 v72, v72, v188
	v_add_u32_e32 v73, v73, v188
	v_add_u32_e32 v74, v74, v188
	v_add_u32_e32 v75, v75, v188
	v_add_u32_e32 v76, v76, v188
	v_add_u32_e32 v77, v77, v188
	v_add_u32_e32 v78, v78, v188
	v_add_u32_e32 v79, v79, v188
	global_load_dwordx4 v[0:3], v64, s[18:19]
	global_load_dwordx4 v[4:7], v65, s[18:19]
	global_load_dwordx4 v[8:11], v66, s[18:19]
	global_load_dwordx4 v[12:15], v67, s[18:19]
	global_load_dwordx4 v[16:19], v68, s[18:19]
	global_load_dwordx4 v[20:23], v69, s[18:19]
	global_load_dwordx4 v[24:27], v70, s[18:19]
	global_load_dwordx4 v[28:31], v71, s[18:19]
	global_load_dwordx4 v[32:35], v72, s[18:19]
	global_load_dwordx4 v[36:39], v73, s[18:19]
	global_load_dwordx4 v[40:43], v74, s[18:19]
	global_load_dwordx4 v[44:47], v75, s[18:19]
	global_load_dwordx4 v[48:51], v76, s[18:19]
	global_load_dwordx4 v[52:55], v77, s[18:19]
	global_load_dwordx4 v[56:59], v78, s[18:19]
	global_load_dwordx4 v[60:63], v79, s[18:19]
	s_waitcnt lgkmcnt(0)
	s_waitcnt vmcnt(15)
	v_cvt_pk_f32_fp8_e32 v[168:169], v0
	v_cvt_pk_f32_fp8_sdwa v[170:171], v0 src0_sel:WORD_1
	v_cvt_pk_f32_fp8_e32 v[172:173], v1
	v_cvt_pk_f32_fp8_sdwa v[174:175], v1 src0_sel:WORD_1
	v_cvt_pk_f32_fp8_e32 v[176:177], v2
	v_cvt_pk_f32_fp8_sdwa v[178:179], v2 src0_sel:WORD_1
	v_cvt_pk_f32_fp8_e32 v[180:181], v3
	v_cvt_pk_f32_fp8_sdwa v[182:183], v3 src0_sel:WORD_1
	v_pk_mul_f32 v[144:145], v[168:169], v[112:113] op_sel_hi:[1,0]
	v_pk_mul_f32 v[146:147], v[170:171], v[112:113] op_sel_hi:[1,0]
	v_pk_mul_f32 v[148:149], v[172:173], v[112:113] op_sel_hi:[1,0]
	v_pk_mul_f32 v[150:151], v[174:175], v[112:113] op_sel_hi:[1,0]
	v_pk_mul_f32 v[152:153], v[176:177], v[112:113] op_sel_hi:[1,0]
	v_pk_mul_f32 v[154:155], v[178:179], v[112:113] op_sel_hi:[1,0]
	v_pk_mul_f32 v[156:157], v[180:181], v[112:113] op_sel_hi:[1,0]
	v_pk_mul_f32 v[158:159], v[182:183], v[112:113] op_sel_hi:[1,0]
	s_waitcnt vmcnt(14)
	v_cvt_pk_f32_fp8_e32 v[168:169], v4
	v_cvt_pk_f32_fp8_sdwa v[170:171], v4 src0_sel:WORD_1
	v_cvt_pk_f32_fp8_e32 v[172:173], v5
	v_cvt_pk_f32_fp8_sdwa v[174:175], v5 src0_sel:WORD_1
	v_cvt_pk_f32_fp8_e32 v[176:177], v6
	v_cvt_pk_f32_fp8_sdwa v[178:179], v6 src0_sel:WORD_1
	v_cvt_pk_f32_fp8_e32 v[180:181], v7
	v_cvt_pk_f32_fp8_sdwa v[182:183], v7 src0_sel:WORD_1
	v_pk_fma_f32 v[144:145], v[168:169], v[112:113], v[144:145] op_sel:[0,1,0] op_sel_hi:[1,1,1]
	v_pk_fma_f32 v[146:147], v[170:171], v[112:113], v[146:147] op_sel:[0,1,0] op_sel_hi:[1,1,1]
	v_pk_fma_f32 v[148:149], v[172:173], v[112:113], v[148:149] op_sel:[0,1,0] op_sel_hi:[1,1,1]
	v_pk_fma_f32 v[150:151], v[174:175], v[112:113], v[150:151] op_sel:[0,1,0] op_sel_hi:[1,1,1]
	v_pk_fma_f32 v[152:153], v[176:177], v[112:113], v[152:153] op_sel:[0,1,0] op_sel_hi:[1,1,1]
	v_pk_fma_f32 v[154:155], v[178:179], v[112:113], v[154:155] op_sel:[0,1,0] op_sel_hi:[1,1,1]
	v_pk_fma_f32 v[156:157], v[180:181], v[112:113], v[156:157] op_sel:[0,1,0] op_sel_hi:[1,1,1]
	v_pk_fma_f32 v[158:159], v[182:183], v[112:113], v[158:159] op_sel:[0,1,0] op_sel_hi:[1,1,1]
	s_waitcnt vmcnt(13)
	v_cvt_pk_f32_fp8_e32 v[168:169], v8
	v_cvt_pk_f32_fp8_sdwa v[170:171], v8 src0_sel:WORD_1
	v_cvt_pk_f32_fp8_e32 v[172:173], v9
	v_cvt_pk_f32_fp8_sdwa v[174:175], v9 src0_sel:WORD_1
	v_cvt_pk_f32_fp8_e32 v[176:177], v10
	v_cvt_pk_f32_fp8_sdwa v[178:179], v10 src0_sel:WORD_1
	v_cvt_pk_f32_fp8_e32 v[180:181], v11
	v_cvt_pk_f32_fp8_sdwa v[182:183], v11 src0_sel:WORD_1
	v_pk_fma_f32 v[144:145], v[168:169], v[114:115], v[144:145] op_sel_hi:[1,0,1]
	v_pk_fma_f32 v[146:147], v[170:171], v[114:115], v[146:147] op_sel_hi:[1,0,1]
	v_pk_fma_f32 v[148:149], v[172:173], v[114:115], v[148:149] op_sel_hi:[1,0,1]
	v_pk_fma_f32 v[150:151], v[174:175], v[114:115], v[150:151] op_sel_hi:[1,0,1]
	v_pk_fma_f32 v[152:153], v[176:177], v[114:115], v[152:153] op_sel_hi:[1,0,1]
	v_pk_fma_f32 v[154:155], v[178:179], v[114:115], v[154:155] op_sel_hi:[1,0,1]
	v_pk_fma_f32 v[156:157], v[180:181], v[114:115], v[156:157] op_sel_hi:[1,0,1]
	v_pk_fma_f32 v[158:159], v[182:183], v[114:115], v[158:159] op_sel_hi:[1,0,1]
	s_waitcnt vmcnt(12)
	v_cvt_pk_f32_fp8_e32 v[168:169], v12
	v_cvt_pk_f32_fp8_sdwa v[170:171], v12 src0_sel:WORD_1
	v_cvt_pk_f32_fp8_e32 v[172:173], v13
	v_cvt_pk_f32_fp8_sdwa v[174:175], v13 src0_sel:WORD_1
	v_cvt_pk_f32_fp8_e32 v[176:177], v14
	v_cvt_pk_f32_fp8_sdwa v[178:179], v14 src0_sel:WORD_1
	v_cvt_pk_f32_fp8_e32 v[180:181], v15
	v_cvt_pk_f32_fp8_sdwa v[182:183], v15 src0_sel:WORD_1
	v_pk_fma_f32 v[144:145], v[168:169], v[114:115], v[144:145] op_sel:[0,1,0] op_sel_hi:[1,1,1]
	v_pk_fma_f32 v[146:147], v[170:171], v[114:115], v[146:147] op_sel:[0,1,0] op_sel_hi:[1,1,1]
	v_pk_fma_f32 v[148:149], v[172:173], v[114:115], v[148:149] op_sel:[0,1,0] op_sel_hi:[1,1,1]
	v_pk_fma_f32 v[150:151], v[174:175], v[114:115], v[150:151] op_sel:[0,1,0] op_sel_hi:[1,1,1]
	v_pk_fma_f32 v[152:153], v[176:177], v[114:115], v[152:153] op_sel:[0,1,0] op_sel_hi:[1,1,1]
	v_pk_fma_f32 v[154:155], v[178:179], v[114:115], v[154:155] op_sel:[0,1,0] op_sel_hi:[1,1,1]
	v_pk_fma_f32 v[156:157], v[180:181], v[114:115], v[156:157] op_sel:[0,1,0] op_sel_hi:[1,1,1]
	v_pk_fma_f32 v[158:159], v[182:183], v[114:115], v[158:159] op_sel:[0,1,0] op_sel_hi:[1,1,1]
	s_waitcnt vmcnt(11)
	v_cvt_pk_f32_fp8_e32 v[168:169], v16
	v_cvt_pk_f32_fp8_sdwa v[170:171], v16 src0_sel:WORD_1
	v_cvt_pk_f32_fp8_e32 v[172:173], v17
	v_cvt_pk_f32_fp8_sdwa v[174:175], v17 src0_sel:WORD_1
	v_cvt_pk_f32_fp8_e32 v[176:177], v18
	v_cvt_pk_f32_fp8_sdwa v[178:179], v18 src0_sel:WORD_1
	v_cvt_pk_f32_fp8_e32 v[180:181], v19
	v_cvt_pk_f32_fp8_sdwa v[182:183], v19 src0_sel:WORD_1
	v_pk_fma_f32 v[144:145], v[168:169], v[116:117], v[144:145] op_sel_hi:[1,0,1]
	v_pk_fma_f32 v[146:147], v[170:171], v[116:117], v[146:147] op_sel_hi:[1,0,1]
	v_pk_fma_f32 v[148:149], v[172:173], v[116:117], v[148:149] op_sel_hi:[1,0,1]
	v_pk_fma_f32 v[150:151], v[174:175], v[116:117], v[150:151] op_sel_hi:[1,0,1]
	v_pk_fma_f32 v[152:153], v[176:177], v[116:117], v[152:153] op_sel_hi:[1,0,1]
	v_pk_fma_f32 v[154:155], v[178:179], v[116:117], v[154:155] op_sel_hi:[1,0,1]
	v_pk_fma_f32 v[156:157], v[180:181], v[116:117], v[156:157] op_sel_hi:[1,0,1]
	v_pk_fma_f32 v[158:159], v[182:183], v[116:117], v[158:159] op_sel_hi:[1,0,1]
	s_waitcnt vmcnt(10)
	v_cvt_pk_f32_fp8_e32 v[168:169], v20
	v_cvt_pk_f32_fp8_sdwa v[170:171], v20 src0_sel:WORD_1
	v_cvt_pk_f32_fp8_e32 v[172:173], v21
	v_cvt_pk_f32_fp8_sdwa v[174:175], v21 src0_sel:WORD_1
	v_cvt_pk_f32_fp8_e32 v[176:177], v22
	v_cvt_pk_f32_fp8_sdwa v[178:179], v22 src0_sel:WORD_1
	v_cvt_pk_f32_fp8_e32 v[180:181], v23
	v_cvt_pk_f32_fp8_sdwa v[182:183], v23 src0_sel:WORD_1
	v_pk_fma_f32 v[144:145], v[168:169], v[116:117], v[144:145] op_sel:[0,1,0] op_sel_hi:[1,1,1]
	v_pk_fma_f32 v[146:147], v[170:171], v[116:117], v[146:147] op_sel:[0,1,0] op_sel_hi:[1,1,1]
	v_pk_fma_f32 v[148:149], v[172:173], v[116:117], v[148:149] op_sel:[0,1,0] op_sel_hi:[1,1,1]
	v_pk_fma_f32 v[150:151], v[174:175], v[116:117], v[150:151] op_sel:[0,1,0] op_sel_hi:[1,1,1]
	v_pk_fma_f32 v[152:153], v[176:177], v[116:117], v[152:153] op_sel:[0,1,0] op_sel_hi:[1,1,1]
	v_pk_fma_f32 v[154:155], v[178:179], v[116:117], v[154:155] op_sel:[0,1,0] op_sel_hi:[1,1,1]
	v_pk_fma_f32 v[156:157], v[180:181], v[116:117], v[156:157] op_sel:[0,1,0] op_sel_hi:[1,1,1]
	v_pk_fma_f32 v[158:159], v[182:183], v[116:117], v[158:159] op_sel:[0,1,0] op_sel_hi:[1,1,1]
	s_waitcnt vmcnt(9)
	v_cvt_pk_f32_fp8_e32 v[168:169], v24
	v_cvt_pk_f32_fp8_sdwa v[170:171], v24 src0_sel:WORD_1
	v_cvt_pk_f32_fp8_e32 v[172:173], v25
	v_cvt_pk_f32_fp8_sdwa v[174:175], v25 src0_sel:WORD_1
	v_cvt_pk_f32_fp8_e32 v[176:177], v26
	v_cvt_pk_f32_fp8_sdwa v[178:179], v26 src0_sel:WORD_1
	v_cvt_pk_f32_fp8_e32 v[180:181], v27
	v_cvt_pk_f32_fp8_sdwa v[182:183], v27 src0_sel:WORD_1
	v_pk_fma_f32 v[144:145], v[168:169], v[118:119], v[144:145] op_sel_hi:[1,0,1]
	v_pk_fma_f32 v[146:147], v[170:171], v[118:119], v[146:147] op_sel_hi:[1,0,1]
	v_pk_fma_f32 v[148:149], v[172:173], v[118:119], v[148:149] op_sel_hi:[1,0,1]
	v_pk_fma_f32 v[150:151], v[174:175], v[118:119], v[150:151] op_sel_hi:[1,0,1]
	v_pk_fma_f32 v[152:153], v[176:177], v[118:119], v[152:153] op_sel_hi:[1,0,1]
	v_pk_fma_f32 v[154:155], v[178:179], v[118:119], v[154:155] op_sel_hi:[1,0,1]
	v_pk_fma_f32 v[156:157], v[180:181], v[118:119], v[156:157] op_sel_hi:[1,0,1]
	v_pk_fma_f32 v[158:159], v[182:183], v[118:119], v[158:159] op_sel_hi:[1,0,1]
	s_waitcnt vmcnt(8)
	v_cvt_pk_f32_fp8_e32 v[168:169], v28
	v_cvt_pk_f32_fp8_sdwa v[170:171], v28 src0_sel:WORD_1
	v_cvt_pk_f32_fp8_e32 v[172:173], v29
	v_cvt_pk_f32_fp8_sdwa v[174:175], v29 src0_sel:WORD_1
	v_cvt_pk_f32_fp8_e32 v[176:177], v30
	v_cvt_pk_f32_fp8_sdwa v[178:179], v30 src0_sel:WORD_1
	v_cvt_pk_f32_fp8_e32 v[180:181], v31
	v_cvt_pk_f32_fp8_sdwa v[182:183], v31 src0_sel:WORD_1
	v_pk_fma_f32 v[144:145], v[168:169], v[118:119], v[144:145] op_sel:[0,1,0] op_sel_hi:[1,1,1]
	v_pk_fma_f32 v[146:147], v[170:171], v[118:119], v[146:147] op_sel:[0,1,0] op_sel_hi:[1,1,1]
	v_pk_fma_f32 v[148:149], v[172:173], v[118:119], v[148:149] op_sel:[0,1,0] op_sel_hi:[1,1,1]
	v_pk_fma_f32 v[150:151], v[174:175], v[118:119], v[150:151] op_sel:[0,1,0] op_sel_hi:[1,1,1]
	v_pk_fma_f32 v[152:153], v[176:177], v[118:119], v[152:153] op_sel:[0,1,0] op_sel_hi:[1,1,1]
	v_pk_fma_f32 v[154:155], v[178:179], v[118:119], v[154:155] op_sel:[0,1,0] op_sel_hi:[1,1,1]
	v_pk_fma_f32 v[156:157], v[180:181], v[118:119], v[156:157] op_sel:[0,1,0] op_sel_hi:[1,1,1]
	v_pk_fma_f32 v[158:159], v[182:183], v[118:119], v[158:159] op_sel:[0,1,0] op_sel_hi:[1,1,1]
	s_waitcnt vmcnt(7)
	v_cvt_pk_f32_fp8_e32 v[168:169], v32
	v_cvt_pk_f32_fp8_sdwa v[170:171], v32 src0_sel:WORD_1
	v_cvt_pk_f32_fp8_e32 v[172:173], v33
	v_cvt_pk_f32_fp8_sdwa v[174:175], v33 src0_sel:WORD_1
	v_cvt_pk_f32_fp8_e32 v[176:177], v34
	v_cvt_pk_f32_fp8_sdwa v[178:179], v34 src0_sel:WORD_1
	v_cvt_pk_f32_fp8_e32 v[180:181], v35
	v_cvt_pk_f32_fp8_sdwa v[182:183], v35 src0_sel:WORD_1
	v_pk_fma_f32 v[144:145], v[168:169], v[120:121], v[144:145] op_sel_hi:[1,0,1]
	v_pk_fma_f32 v[146:147], v[170:171], v[120:121], v[146:147] op_sel_hi:[1,0,1]
	v_pk_fma_f32 v[148:149], v[172:173], v[120:121], v[148:149] op_sel_hi:[1,0,1]
	v_pk_fma_f32 v[150:151], v[174:175], v[120:121], v[150:151] op_sel_hi:[1,0,1]
	v_pk_fma_f32 v[152:153], v[176:177], v[120:121], v[152:153] op_sel_hi:[1,0,1]
	v_pk_fma_f32 v[154:155], v[178:179], v[120:121], v[154:155] op_sel_hi:[1,0,1]
	v_pk_fma_f32 v[156:157], v[180:181], v[120:121], v[156:157] op_sel_hi:[1,0,1]
	v_pk_fma_f32 v[158:159], v[182:183], v[120:121], v[158:159] op_sel_hi:[1,0,1]
	s_waitcnt vmcnt(6)
	v_cvt_pk_f32_fp8_e32 v[168:169], v36
	v_cvt_pk_f32_fp8_sdwa v[170:171], v36 src0_sel:WORD_1
	v_cvt_pk_f32_fp8_e32 v[172:173], v37
	v_cvt_pk_f32_fp8_sdwa v[174:175], v37 src0_sel:WORD_1
	v_cvt_pk_f32_fp8_e32 v[176:177], v38
	v_cvt_pk_f32_fp8_sdwa v[178:179], v38 src0_sel:WORD_1
	v_cvt_pk_f32_fp8_e32 v[180:181], v39
	v_cvt_pk_f32_fp8_sdwa v[182:183], v39 src0_sel:WORD_1
	v_pk_fma_f32 v[144:145], v[168:169], v[120:121], v[144:145] op_sel:[0,1,0] op_sel_hi:[1,1,1]
	v_pk_fma_f32 v[146:147], v[170:171], v[120:121], v[146:147] op_sel:[0,1,0] op_sel_hi:[1,1,1]
	v_pk_fma_f32 v[148:149], v[172:173], v[120:121], v[148:149] op_sel:[0,1,0] op_sel_hi:[1,1,1]
	v_pk_fma_f32 v[150:151], v[174:175], v[120:121], v[150:151] op_sel:[0,1,0] op_sel_hi:[1,1,1]
	v_pk_fma_f32 v[152:153], v[176:177], v[120:121], v[152:153] op_sel:[0,1,0] op_sel_hi:[1,1,1]
	v_pk_fma_f32 v[154:155], v[178:179], v[120:121], v[154:155] op_sel:[0,1,0] op_sel_hi:[1,1,1]
	v_pk_fma_f32 v[156:157], v[180:181], v[120:121], v[156:157] op_sel:[0,1,0] op_sel_hi:[1,1,1]
	v_pk_fma_f32 v[158:159], v[182:183], v[120:121], v[158:159] op_sel:[0,1,0] op_sel_hi:[1,1,1]
	s_waitcnt vmcnt(5)
	v_cvt_pk_f32_fp8_e32 v[168:169], v40
	v_cvt_pk_f32_fp8_sdwa v[170:171], v40 src0_sel:WORD_1
	v_cvt_pk_f32_fp8_e32 v[172:173], v41
	v_cvt_pk_f32_fp8_sdwa v[174:175], v41 src0_sel:WORD_1
	v_cvt_pk_f32_fp8_e32 v[176:177], v42
	v_cvt_pk_f32_fp8_sdwa v[178:179], v42 src0_sel:WORD_1
	v_cvt_pk_f32_fp8_e32 v[180:181], v43
	v_cvt_pk_f32_fp8_sdwa v[182:183], v43 src0_sel:WORD_1
	v_pk_fma_f32 v[144:145], v[168:169], v[122:123], v[144:145] op_sel_hi:[1,0,1]
	v_pk_fma_f32 v[146:147], v[170:171], v[122:123], v[146:147] op_sel_hi:[1,0,1]
	v_pk_fma_f32 v[148:149], v[172:173], v[122:123], v[148:149] op_sel_hi:[1,0,1]
	v_pk_fma_f32 v[150:151], v[174:175], v[122:123], v[150:151] op_sel_hi:[1,0,1]
	v_pk_fma_f32 v[152:153], v[176:177], v[122:123], v[152:153] op_sel_hi:[1,0,1]
	v_pk_fma_f32 v[154:155], v[178:179], v[122:123], v[154:155] op_sel_hi:[1,0,1]
	v_pk_fma_f32 v[156:157], v[180:181], v[122:123], v[156:157] op_sel_hi:[1,0,1]
	v_pk_fma_f32 v[158:159], v[182:183], v[122:123], v[158:159] op_sel_hi:[1,0,1]
	s_waitcnt vmcnt(4)
	v_cvt_pk_f32_fp8_e32 v[168:169], v44
	v_cvt_pk_f32_fp8_sdwa v[170:171], v44 src0_sel:WORD_1
	v_cvt_pk_f32_fp8_e32 v[172:173], v45
	v_cvt_pk_f32_fp8_sdwa v[174:175], v45 src0_sel:WORD_1
	v_cvt_pk_f32_fp8_e32 v[176:177], v46
	v_cvt_pk_f32_fp8_sdwa v[178:179], v46 src0_sel:WORD_1
	v_cvt_pk_f32_fp8_e32 v[180:181], v47
	v_cvt_pk_f32_fp8_sdwa v[182:183], v47 src0_sel:WORD_1
	v_pk_fma_f32 v[144:145], v[168:169], v[122:123], v[144:145] op_sel:[0,1,0] op_sel_hi:[1,1,1]
	v_pk_fma_f32 v[146:147], v[170:171], v[122:123], v[146:147] op_sel:[0,1,0] op_sel_hi:[1,1,1]
	v_pk_fma_f32 v[148:149], v[172:173], v[122:123], v[148:149] op_sel:[0,1,0] op_sel_hi:[1,1,1]
	v_pk_fma_f32 v[150:151], v[174:175], v[122:123], v[150:151] op_sel:[0,1,0] op_sel_hi:[1,1,1]
	v_pk_fma_f32 v[152:153], v[176:177], v[122:123], v[152:153] op_sel:[0,1,0] op_sel_hi:[1,1,1]
	v_pk_fma_f32 v[154:155], v[178:179], v[122:123], v[154:155] op_sel:[0,1,0] op_sel_hi:[1,1,1]
	v_pk_fma_f32 v[156:157], v[180:181], v[122:123], v[156:157] op_sel:[0,1,0] op_sel_hi:[1,1,1]
	v_pk_fma_f32 v[158:159], v[182:183], v[122:123], v[158:159] op_sel:[0,1,0] op_sel_hi:[1,1,1]
	s_waitcnt vmcnt(3)
	v_cvt_pk_f32_fp8_e32 v[168:169], v48
	v_cvt_pk_f32_fp8_sdwa v[170:171], v48 src0_sel:WORD_1
	v_cvt_pk_f32_fp8_e32 v[172:173], v49
	v_cvt_pk_f32_fp8_sdwa v[174:175], v49 src0_sel:WORD_1
	v_cvt_pk_f32_fp8_e32 v[176:177], v50
	v_cvt_pk_f32_fp8_sdwa v[178:179], v50 src0_sel:WORD_1
	v_cvt_pk_f32_fp8_e32 v[180:181], v51
	v_cvt_pk_f32_fp8_sdwa v[182:183], v51 src0_sel:WORD_1
	v_pk_fma_f32 v[144:145], v[168:169], v[124:125], v[144:145] op_sel_hi:[1,0,1]
	v_pk_fma_f32 v[146:147], v[170:171], v[124:125], v[146:147] op_sel_hi:[1,0,1]
	v_pk_fma_f32 v[148:149], v[172:173], v[124:125], v[148:149] op_sel_hi:[1,0,1]
	v_pk_fma_f32 v[150:151], v[174:175], v[124:125], v[150:151] op_sel_hi:[1,0,1]
	v_pk_fma_f32 v[152:153], v[176:177], v[124:125], v[152:153] op_sel_hi:[1,0,1]
	v_pk_fma_f32 v[154:155], v[178:179], v[124:125], v[154:155] op_sel_hi:[1,0,1]
	v_pk_fma_f32 v[156:157], v[180:181], v[124:125], v[156:157] op_sel_hi:[1,0,1]
	v_pk_fma_f32 v[158:159], v[182:183], v[124:125], v[158:159] op_sel_hi:[1,0,1]
	s_waitcnt vmcnt(2)
	v_cvt_pk_f32_fp8_e32 v[168:169], v52
	v_cvt_pk_f32_fp8_sdwa v[170:171], v52 src0_sel:WORD_1
	v_cvt_pk_f32_fp8_e32 v[172:173], v53
	v_cvt_pk_f32_fp8_sdwa v[174:175], v53 src0_sel:WORD_1
	v_cvt_pk_f32_fp8_e32 v[176:177], v54
	v_cvt_pk_f32_fp8_sdwa v[178:179], v54 src0_sel:WORD_1
	v_cvt_pk_f32_fp8_e32 v[180:181], v55
	v_cvt_pk_f32_fp8_sdwa v[182:183], v55 src0_sel:WORD_1
	v_pk_fma_f32 v[144:145], v[168:169], v[124:125], v[144:145] op_sel:[0,1,0] op_sel_hi:[1,1,1]
	v_pk_fma_f32 v[146:147], v[170:171], v[124:125], v[146:147] op_sel:[0,1,0] op_sel_hi:[1,1,1]
	v_pk_fma_f32 v[148:149], v[172:173], v[124:125], v[148:149] op_sel:[0,1,0] op_sel_hi:[1,1,1]
	v_pk_fma_f32 v[150:151], v[174:175], v[124:125], v[150:151] op_sel:[0,1,0] op_sel_hi:[1,1,1]
	v_pk_fma_f32 v[152:153], v[176:177], v[124:125], v[152:153] op_sel:[0,1,0] op_sel_hi:[1,1,1]
	v_pk_fma_f32 v[154:155], v[178:179], v[124:125], v[154:155] op_sel:[0,1,0] op_sel_hi:[1,1,1]
	v_pk_fma_f32 v[156:157], v[180:181], v[124:125], v[156:157] op_sel:[0,1,0] op_sel_hi:[1,1,1]
	v_pk_fma_f32 v[158:159], v[182:183], v[124:125], v[158:159] op_sel:[0,1,0] op_sel_hi:[1,1,1]
	s_waitcnt vmcnt(1)
	v_cvt_pk_f32_fp8_e32 v[168:169], v56
	v_cvt_pk_f32_fp8_sdwa v[170:171], v56 src0_sel:WORD_1
	v_cvt_pk_f32_fp8_e32 v[172:173], v57
	v_cvt_pk_f32_fp8_sdwa v[174:175], v57 src0_sel:WORD_1
	v_cvt_pk_f32_fp8_e32 v[176:177], v58
	v_cvt_pk_f32_fp8_sdwa v[178:179], v58 src0_sel:WORD_1
	v_cvt_pk_f32_fp8_e32 v[180:181], v59
	v_cvt_pk_f32_fp8_sdwa v[182:183], v59 src0_sel:WORD_1
	v_pk_fma_f32 v[144:145], v[168:169], v[126:127], v[144:145] op_sel_hi:[1,0,1]
	v_pk_fma_f32 v[146:147], v[170:171], v[126:127], v[146:147] op_sel_hi:[1,0,1]
	v_pk_fma_f32 v[148:149], v[172:173], v[126:127], v[148:149] op_sel_hi:[1,0,1]
	v_pk_fma_f32 v[150:151], v[174:175], v[126:127], v[150:151] op_sel_hi:[1,0,1]
	v_pk_fma_f32 v[152:153], v[176:177], v[126:127], v[152:153] op_sel_hi:[1,0,1]
	v_pk_fma_f32 v[154:155], v[178:179], v[126:127], v[154:155] op_sel_hi:[1,0,1]
	v_pk_fma_f32 v[156:157], v[180:181], v[126:127], v[156:157] op_sel_hi:[1,0,1]
	v_pk_fma_f32 v[158:159], v[182:183], v[126:127], v[158:159] op_sel_hi:[1,0,1]
	s_waitcnt vmcnt(0)
	v_cvt_pk_f32_fp8_e32 v[168:169], v60
	v_cvt_pk_f32_fp8_sdwa v[170:171], v60 src0_sel:WORD_1
	v_cvt_pk_f32_fp8_e32 v[172:173], v61
	v_cvt_pk_f32_fp8_sdwa v[174:175], v61 src0_sel:WORD_1
	v_cvt_pk_f32_fp8_e32 v[176:177], v62
	v_cvt_pk_f32_fp8_sdwa v[178:179], v62 src0_sel:WORD_1
	v_cvt_pk_f32_fp8_e32 v[180:181], v63
	v_cvt_pk_f32_fp8_sdwa v[182:183], v63 src0_sel:WORD_1
	v_pk_fma_f32 v[144:145], v[168:169], v[126:127], v[144:145] op_sel:[0,1,0] op_sel_hi:[1,1,1]
	v_pk_fma_f32 v[146:147], v[170:171], v[126:127], v[146:147] op_sel:[0,1,0] op_sel_hi:[1,1,1]
	v_pk_fma_f32 v[148:149], v[172:173], v[126:127], v[148:149] op_sel:[0,1,0] op_sel_hi:[1,1,1]
	v_pk_fma_f32 v[150:151], v[174:175], v[126:127], v[150:151] op_sel:[0,1,0] op_sel_hi:[1,1,1]
	v_pk_fma_f32 v[152:153], v[176:177], v[126:127], v[152:153] op_sel:[0,1,0] op_sel_hi:[1,1,1]
	v_pk_fma_f32 v[154:155], v[178:179], v[126:127], v[154:155] op_sel:[0,1,0] op_sel_hi:[1,1,1]
	v_pk_fma_f32 v[156:157], v[180:181], v[126:127], v[156:157] op_sel:[0,1,0] op_sel_hi:[1,1,1]
	v_pk_fma_f32 v[158:159], v[182:183], v[126:127], v[158:159] op_sel:[0,1,0] op_sel_hi:[1,1,1]
	s_nop 1
	v_permlane32_swap_b32_e32 v144, v152
	v_permlane32_swap_b32_e32 v145, v153
	v_permlane32_swap_b32_e32 v146, v154
	v_permlane32_swap_b32_e32 v147, v155
	v_permlane32_swap_b32_e32 v148, v156
	v_permlane32_swap_b32_e32 v149, v157
	v_permlane32_swap_b32_e32 v150, v158
	v_permlane32_swap_b32_e32 v151, v159
	v_add_f32_e32 v144, v144, v152
	v_add_f32_e32 v145, v145, v153
	v_add_f32_e32 v146, v146, v154
	v_add_f32_e32 v147, v147, v155
	v_add_f32_e32 v148, v148, v156
	v_add_f32_e32 v149, v149, v157
	v_add_f32_e32 v150, v150, v158
	v_add_f32_e32 v151, v151, v159
	s_nop 1
	v_permlane16_swap_b32_e32 v144, v148
	v_permlane16_swap_b32_e32 v145, v149
	v_permlane16_swap_b32_e32 v146, v150
	v_permlane16_swap_b32_e32 v147, v151
	v_add_f32_e32 v144, v144, v148
	v_add_f32_e32 v145, v145, v149
	v_add_f32_e32 v146, v146, v150
	v_add_f32_e32 v147, v147, v151
	s_nop 1
	v_add_f32_dpp v148, v144, v144 row_ror:8 row_mask:0xf bank_mask:0x3
	v_add_f32_dpp v149, v145, v145 row_ror:8 row_mask:0xf bank_mask:0x3
	v_add_f32_dpp v148, v146, v146 row_ror:8 row_mask:0xf bank_mask:0xc
	v_add_f32_dpp v149, v147, v147 row_ror:8 row_mask:0xf bank_mask:0xc
	s_waitcnt vmcnt(0)
	v_add_f32_e32 v208, v208, v148
	v_add_f32_e32 v209, v209, v149
	global_store_dwordx2 v211, v[208:209], s[20:21]
	v_cvt_pk_bf16_f32 v212, v208, v209
	v_mul_f32_e32 v193, v208, v208
	v_fmac_f32_e32 v193, v209, v209
	global_store_dword v213, v212, s[36:37]
	s_cmp_eq_u32 s17, 8
	s_cbranch_scc1 .Lpc_xacc
	ds_add_f32 v206, v193 offset:9216
	s_branch .Lpc_xdone

.Lpd_tok:
	s_lshl_b32 s25, s17, 9
	v_add_u32_e32 v206, s25, v202
	ds_read_b32 v16, v206 offset:9216
	s_lshl_b32 s0, s17, 11
	s_add_i32 s0, s0, s27
	s_lshl_b32 s0, s0, 2
	s_add_u32 s20, s14, s0
	s_addc_u32 s21, s15, 0
	s_waitcnt lgkmcnt(0)
	s_nop 1
	v_add_f32_dpp v17, v16, v16 quad_perm:[1,0,3,2] row_mask:0xf bank_mask:0xf
	s_nop 1
	v_add_f32_dpp v16, v17, v17 quad_perm:[2,3,0,1] row_mask:0xf bank_mask:0xf
	s_nop 1
	v_add_f32_dpp v17, v16, v16 row_half_mirror row_mask:0xf bank_mask:0xf
	s_nop 1
	v_add_f32_dpp v16, v17, v17 row_mirror row_mask:0xf bank_mask:0xf
	s_nop 1
	v_readlane_b32 s0, v16, 0
	v_readlane_b32 s1, v16, 16
	v_readlane_b32 s22, v16, 32
	v_readlane_b32 s23, v16, 48
	s_nop 1
	v_mov_b32_e32 v16, s0
	v_add_f32_e32 v16, s1, v16
	v_add_f32_e32 v16, s22, v16
	v_add_f32_e32 v16, s23, v16
	v_fmamk_f32 v16, v16, 0x3a800000, v198
	v_mul_f32_e32 v17, 0x4b800000, v16
	v_cmp_gt_f32_e32 vcc, s35, v16
	s_nop 1
	v_cndmask_b32_e32 v16, v16, v17, vcc
	v_rsq_f32_e32 v16, v16
	s_nop 0
	v_mul_f32_e32 v17, 0x45800000, v16
	v_cndmask_b32_e32 v18, v16, v17, vcc
	global_store_dword v203, v18, s[20:21]
	s_add_i32 s17, s17, 1
	s_cmp_lt_i32 s17, 8
	s_cbranch_scc1 .Lpd_tok
	s_nop 1
	v_add_f32_dpp v17, v194, v194 quad_perm:[1,0,3,2] row_mask:0xf bank_mask:0xf
	s_nop 1
	v_add_f32_dpp v194, v17, v17 quad_perm:[2,3,0,1] row_mask:0xf bank_mask:0xf
	s_nop 1
	v_add_f32_dpp v17, v194, v194 row_half_mirror row_mask:0xf bank_mask:0xf
	s_nop 1
	v_add_f32_dpp v194, v17, v17 row_mirror row_mask:0xf bank_mask:0xf
	s_nop 1
	v_readlane_b32 s0, v194, 0
	v_readlane_b32 s1, v194, 16
	v_readlane_b32 s22, v194, 32
	v_readlane_b32 s23, v194, 48
	s_nop 1
	v_mov_b32_e32 v194, s0
	v_add_f32_e32 v194, s1, v194
	v_add_f32_e32 v194, s22, v194
	v_add_f32_e32 v194, s23, v194
	v_mov_b32_e32 v16, 0x4a30
	v_lshl_add_u32 v19, v214, 2, v16
	ds_write_b32 v19, v194
	s_waitcnt lgkmcnt(0)
	s_barrier
	ds_read_b128 v[20:23], v16
	s_lshl_b32 s0, s44, 2
	s_add_u32 s20, s14, s0
	s_addc_u32 s21, s15, 0
	s_waitcnt lgkmcnt(0)
	v_add_f32_e32 v16, v20, v21
	v_add_f32_e32 v16, v16, v22
	v_add_f32_e32 v16, v16, v23
	v_fmamk_f32 v16, v16, 0x3a800000, v198
	v_mul_f32_e32 v17, 0x4b800000, v16
	v_cmp_gt_f32_e32 vcc, s35, v16
	s_nop 1
	v_cndmask_b32_e32 v16, v16, v17, vcc
	v_rsq_f32_e32 v16, v16
	s_nop 0
	v_mul_f32_e32 v17, 0x45800000, v16
	v_cndmask_b32_e32 v18, v16, v17, vcc
	global_store_dword v203, v18, s[20:21]
